# attention unit prologue: first K/V tile loads no longer waited before issuing the Q and tile 1-3 loads (one round trip instead of two)
# baseline (speedup 1.0000x reference)
; DI unsigned pk2(float lo, float hi) { f32x2_t v = {lo, hi}; bf16x2_t b = __builtin_convertvector(v, bf16x2_t); return __builtin_bit_cast(unsigned, b); }
; DI float bflo(unsigned u) { return __uint_as_float(u << 16); }
; DI float bfhi(unsigned u) { return __uint_as_float(u & 0xffff0000u); }
; DI void attn_unit(int b, int h, int qb, const bf16* Qb, const bf16* Kb, const bf16* Vt, const int* positions, bf16* O, LAS unsigned char* lds, int tid) {
;     const int wave = __builtin_amdgcn_readfirstlane(tid >> 6), lane = tid & 63, r32 = lane & 31, hi = lane >> 5;
;     const int rowbase = b * T, q0 = qb * 256, qrow = q0 + 32 * wave + r32;
;     const int kkey0 = tid / 12, kc0 = tid % 12, vd = tid >> 3, vc = tid & 7;
;     const bf16* kg0 = Kb + (size_t)(rowbase + kkey0) * 768 + h * 96 + kc0 * 8;
;     const bf16* vg = Vt + (size_t)(h * 64 + vd) * VT_LD + rowbase + vc * 8;
;     const int NT = (q0 + 256) / 64, NTF = q0 / 64;
;     const int kp1 = tid < 256 ? 512 + tid : tid;
;     const int kkey1 = kp1 / 12, kc1 = kp1 % 12;
;     const bf16* kg1 = Kb + (size_t)(rowbase + kkey1) * 768 + h * 96 + kc1 * 8;
;     u32x4 kA0, kA1, vA, kB0, kB1, vB, kC0, kC1, vC;
;     ...
;     AT_ISSUE(A, 0); AT_ISSUE(B, 1); AT_ISSUE(C, 2);
;     bf16x8 qr[6];
;     {
;         const bf16* qp = Qb + (size_t)(rowbase + qrow) * 768 + h * 96 + 8 * hi;
;         float qv[6][8];
; #pragma unroll
;         for (int d0 = 0; d0 < 6; ++d0) { const u32x4 a = *(const u32x4*)(qp + 16 * d0);
;             qv[d0][0] = bflo(a.x); qv[d0][1] = bfhi(a.x); qv[d0][2] = bflo(a.y); qv[d0][3] = bfhi(a.y); qv[d0][4] = bflo(a.z); qv[d0][5] = bfhi(a.z); qv[d0][6] = bflo(a.w); qv[d0][7] = bfhi(a.w); }
;         const int pos = positions[rowbase + qrow];
; #pragma unroll
;         for (int i = 0; i < 8; ++i) { float c, s; rope_cs(pos, 8 * hi + i, c, s); const float x1 = qv[4][i], x2 = qv[5][i]; qv[4][i] = x1 * c - x2 * s; qv[5][i] = x1 * s + x2 * c; }
;         const float C2 = 0.10206207261596575f * 1.4426950408889634f;
; #pragma unroll
;         for (int d0 = 0; d0 < 6; ++d0) { u32x4 p; p.x = pk2(qv[d0][0] * C2, qv[d0][1] * C2); p.y = pk2(qv[d0][2] * C2, qv[d0][3] * C2); p.z = pk2(qv[d0][4] * C2, qv[d0][5] * C2); p.w = pk2(qv[d0][6] * C2, qv[d0][7] * C2);
;             qr[d0] = __builtin_bit_cast(bf16x8, p); }
;     }
;     AT_COMMIT(A, 0);
;     AT_ISSUE(A, 3);
.LBB0_845:
	s_or_b64 exec, exec, s[18:19]
	s_and_b32 s18, s12, 7
	s_or_b32 s20, s18, s25
	s_and_b32 s21, s12, 63
	s_and_b64 s[18:19], s[8:9], exec
	s_cselect_b32 s18, s20, s21
	s_ashr_i32 s12, s12, s26
	s_sub_i32 s22, 15, s12
	s_lshl_b32 s12, s18, 9
	s_and_b32 s34, s12, 0xfffff000
	v_or_b32_e32 v0, s34, v202
	s_and_b32 s20, s18, 7
	v_mad_i64_i32 v[2:3], s[18:19], v0, s27, v[186:187]
	s_lshl_b32 s18, s20, 6
	s_mul_i32 s12, s20, 0x60
	v_add_u32_e32 v0, s18, v198
	s_lshl_b32 s12, s12, 1
	v_mul_u32_u24_e32 v0, 0x8040, v0
	v_lshl_add_u64 v[2:3], v[2:3], 0, s[12:13]
	v_lshlrev_b32_e32 v0, 1, v0
	s_lshl_b32 s23, s22, 8
	v_lshl_add_u64 v[190:191], v[2:3], 0, v[182:183]
	v_lshl_add_u64 v[2:3], s[6:7], 0, v[0:1]
	s_ashr_i32 s35, s34, 31
	v_lshl_add_u64 v[2:3], s[34:35], 1, v[2:3]
	v_mov_b32_e32 v159, v1
	s_add_i32 s19, s23, 0x100
	v_or_b32_e32 v0, s34, v203
	v_lshl_add_u64 v[192:193], v[2:3], 0, v[158:159]
	s_ashr_i32 s19, s19, 6
	v_mad_i64_i32 v[2:3], s[20:21], v0, s27, v[186:187]
	v_lshl_add_u64 v[2:3], v[2:3], 0, s[12:13]
	v_mov_b32_e32 v185, v1
	s_add_i32 s20, s19, -1
	v_lshl_add_u64 v[194:195], v[2:3], 0, v[184:185]
	s_min_i32 s21, s20, 0
	v_mad_i64_i32 v[2:3], s[36:37], s21, v161, v[190:191]
	v_mad_i64_i32 v[6:7], s[36:37], s21, v161, v[194:195]
	s_lshl_b32 s36, s21, 6
	s_ashr_i32 s37, s36, 31
	v_lshl_add_u64 v[10:11], s[36:37], 1, v[192:193]
	global_load_dwordx4 v[214:217], v[2:3], off
	s_nop 0
	global_load_dwordx4 v[218:221], v[6:7], off
	s_nop 0
	global_load_dwordx4 v[222:225], v[10:11], off
	v_readfirstlane_b32 s21, v197
	s_lshr_b32 s21, s21, 1
	s_and_b32 s21, s21, 0x7fffffe0
	s_add_i32 s23, s21, s23
	v_or_b32_e32 v49, s23, v201
	v_add_u32_e32 v188, s34, v49
	v_ashrrev_i32_e32 v189, 31, v188
	s_cmp_lt_i32 s19, 1
	s_mov_b32 s21, 0
	s_cbranch_scc1 .LBB0_868
	v_readlane_b32 s36, v253, 3
	v_readlane_b32 s38, v253, 5
	v_readlane_b32 s39, v253, 6
	s_min_i32 s33, s20, 1
	v_readlane_b32 s37, v253, 4
	v_lshl_add_u64 v[2:3], v[188:189], 2, s[38:39]
	global_load_dword v0, v[2:3], off
	v_lshl_add_u64 v[2:3], v[162:163], 0, s[12:13]
	v_mad_i64_i32 v[2:3], s[34:35], v188, s27, v[2:3]
	global_load_dwordx4 v[14:17], v[2:3], off offset:96
	global_load_dwordx4 v[18:21], v[2:3], off offset:128
	global_load_dwordx4 v[22:25], v[2:3], off offset:160
	s_min_i32 s38, s20, 2
	v_mad_i64_i32 v[26:27], s[34:35], s33, v161, v[190:191]
	v_mad_i64_i32 v[4:5], s[34:35], s33, v161, v[194:195]
	s_lshl_b32 s34, s33, 6
	v_mad_i64_i32 v[6:7], s[36:37], s38, v161, v[190:191]
	v_mad_i64_i32 v[8:9], s[36:37], s38, v161, v[194:195]
	s_lshl_b32 s36, s38, 6
	s_ashr_i32 s35, s34, 31
	s_ashr_i32 s37, s36, 31
	v_lshl_add_u64 v[28:29], s[34:35], 1, v[192:193]
	global_load_dwordx4 v[98:101], v[6:7], off
	global_load_dwordx4 v[102:105], v[8:9], off
	s_nop 0
	global_load_dwordx4 v[6:9], v[2:3], off offset:32
	global_load_dwordx4 v[10:13], v[2:3], off offset:64
	v_lshl_add_u64 v[30:31], s[36:37], 1, v[192:193]
	global_load_dwordx4 v[106:109], v[4:5], off
	global_load_dwordx4 v[110:113], v[28:29], off
	global_load_dwordx4 v[114:117], v[30:31], off
	s_nop 0
	global_load_dwordx4 v[2:5], v[2:3], off
	s_nop 0
	global_load_dwordx4 v[130:133], v[26:27], off
	global_load_dwordx4 v[134:137], v[192:193], off offset:384
	s_waitcnt vmcnt(16)
	ds_write_b128 v209, v[214:217]
	s_waitcnt vmcnt(15)
	ds_write_b128 v210, v[218:221]
	s_waitcnt vmcnt(14)
	ds_write2_b64 v211, v[222:223], v[224:225] offset1:1
	s_lshl_b32 s12, s22, 2
	s_or_b32 s22, s23, 31
	v_mov_b32_e32 v48, 0
	s_mov_b32 s23, 0
	v_readlane_b32 s40, v253, 7
	v_readlane_b32 s41, v253, 8
	v_readlane_b32 s42, v253, 9
	v_readlane_b32 s43, v253, 10
	v_readlane_b32 s44, v253, 11
	v_readlane_b32 s45, v253, 12
	v_readlane_b32 s46, v253, 13
	v_readlane_b32 s47, v253, 14
	v_readlane_b32 s48, v253, 15
	v_readlane_b32 s49, v253, 16
	v_readlane_b32 s50, v253, 17
	v_readlane_b32 s51, v253, 18
	s_waitcnt vmcnt(13)
	v_cvt_f64_i32_e32 v[28:29], v0
	v_mul_f64 v[30:31], v[164:165], v[28:29]
	v_mul_f64 v[32:33], v[166:167], v[28:29]
	v_mul_f64 v[44:45], v[30:31], s[14:15]
	v_mul_f64 v[46:47], v[32:33], s[14:15]
	v_rndne_f64_e32 v[44:45], v[44:45]
	v_rndne_f64_e32 v[46:47], v[46:47]
	v_fma_f64 v[30:31], v[30:31], s[14:15], -v[44:45]
	v_fma_f64 v[32:33], v[32:33], s[14:15], -v[46:47]
	v_mul_f64 v[34:35], v[168:169], v[28:29]
	v_mul_f64 v[36:37], v[170:171], v[28:29]
	v_cvt_f32_f64_e32 v0, v[30:31]
	v_cvt_f32_f64_e32 v33, v[32:33]
	v_mul_f64 v[38:39], v[172:173], v[28:29]
	v_mul_f64 v[40:41], v[174:175], v[28:29]
	v_mul_f64 v[42:43], v[176:177], v[28:29]
	v_mul_f64 v[28:29], v[178:179], v[28:29]
	v_mul_f64 v[50:51], v[34:35], s[14:15]
	v_mul_f64 v[52:53], v[36:37], s[14:15]
	v_cos_f32_e32 v32, v0
	v_sin_f32_e32 v31, v33
	v_cos_f32_e32 v33, v33
	v_mul_f64 v[60:61], v[28:29], s[14:15]
	v_rndne_f64_e32 v[50:51], v[50:51]
	v_rndne_f64_e32 v[52:53], v[52:53]
	v_sin_f32_e32 v30, v0
	v_rndne_f64_e32 v[60:61], v[60:61]
	v_fma_f64 v[34:35], v[34:35], s[14:15], -v[50:51]
	v_fma_f64 v[36:37], v[36:37], s[14:15], -v[52:53]
	v_mul_f64 v[54:55], v[38:39], s[14:15]
	v_mul_f64 v[56:57], v[40:41], s[14:15]
	v_fma_f64 v[28:29], v[28:29], s[14:15], -v[60:61]
	v_cvt_f32_f64_e32 v35, v[34:35]
	v_cvt_f32_f64_e32 v37, v[36:37]
	s_waitcnt vmcnt(10)
; DI unsigned pk2(float lo, float hi) { f32x2_t v = {lo, hi}; bf16x2_t b = __builtin_convertvector(v, bf16x2_t); return __builtin_bit_cast(unsigned, b); }
; DI float bflo(unsigned u) { return __uint_as_float(u << 16); }
; DI float bfhi(unsigned u) { return __uint_as_float(u & 0xffff0000u); }
; #define AT_ISSUE(S, t) do { const int tt_ = (t) < NT ? (t) : NT - 1; const size_t ko_ = (size_t)tt_ * 64 * 768; \
;         k##S##0 = *(const u32x4*)(kg0 + ko_); k##S##1 = *(const u32x4*)(kg1 + ko_); v##S = *(const u32x4*)(vg + tt_ * 64); } while (0)
; DI void attn_unit(int b, int h, int qb, const bf16* Qb, const bf16* Kb, const bf16* Vt, const int* positions, bf16* O, LAS unsigned char* lds, int tid) {
;     ...
;         for (int d0 = 0; d0 < 6; ++d0) { const u32x4 a = *(const u32x4*)(qp + 16 * d0);
;             qv[d0][0] = bflo(a.x); qv[d0][1] = bfhi(a.x); qv[d0][2] = bflo(a.y); qv[d0][3] = bfhi(a.y); qv[d0][4] = bflo(a.z); qv[d0][5] = bfhi(a.z); qv[d0][6] = bflo(a.w); qv[d0][7] = bfhi(a.w); }
;         const int pos = positions[rowbase + qrow];
; #pragma unroll
;         for (int i = 0; i < 8; ++i) { float c, s; rope_cs(pos, 8 * hi + i, c, s); const float x1 = qv[4][i], x2 = qv[5][i]; qv[4][i] = x1 * c - x2 * s; qv[5][i] = x1 * s + x2 * c; }
;         const float C2 = 0.10206207261596575f * 1.4426950408889634f;
; #pragma unroll
;         for (int d0 = 0; d0 < 6; ++d0) { u32x4 p; p.x = pk2(qv[d0][0] * C2, qv[d0][1] * C2); p.y = pk2(qv[d0][2] * C2, qv[d0][3] * C2); p.z = pk2(qv[d0][4] * C2, qv[d0][5] * C2); p.w = pk2(qv[d0][6] * C2, qv[d0][7] * C2);
;             qr[d0] = __builtin_bit_cast(bf16x8, p); }
;     }
;     AT_COMMIT(A, 0);
;     AT_ISSUE(A, 3);
;     float mrun = 0.f, lrun = 0.f;
;     f32x16 o0 = {}, o1 = {}, negm = {};
	v_lshlrev_b32_e32 v46, 16, v22
	v_and_b32_e32 v47, 0xffff0000, v22
	v_rndne_f64_e32 v[54:55], v[54:55]
	v_rndne_f64_e32 v[56:57], v[56:57]
	v_sin_f32_e32 v34, v35
	v_cos_f32_e32 v36, v35
	v_sin_f32_e32 v35, v37
	v_cos_f32_e32 v37, v37
	v_cvt_f32_f64_e32 v0, v[28:29]
	v_lshlrev_b32_e32 v28, 16, v18
	v_and_b32_e32 v29, 0xffff0000, v18
	v_pk_mul_f32 v[50:51], v[32:33], v[46:47]
	v_fma_f64 v[38:39], v[38:39], s[14:15], -v[54:55]
	v_fma_f64 v[40:41], v[40:41], s[14:15], -v[56:57]
	v_pk_fma_f32 v[50:51], v[30:31], v[28:29], v[50:51]
	v_pk_mul_f32 v[30:31], v[30:31], v[46:47]
	v_cvt_f32_f64_e32 v39, v[38:39]
	v_cvt_f32_f64_e32 v41, v[40:41]
	v_pk_fma_f32 v[28:29], v[32:33], v[28:29], v[30:31] neg_lo:[0,0,1] neg_hi:[0,0,1]
	v_mul_f64 v[58:59], v[42:43], s[14:15]
	v_sin_f32_e32 v38, v39
	v_cos_f32_e32 v40, v39
	v_sin_f32_e32 v39, v41
	v_cos_f32_e32 v41, v41
	v_pk_mul_f32 v[28:29], v[28:29], s[16:17] op_sel_hi:[1,0]
	v_lshlrev_b32_e32 v22, 16, v23
	v_and_b32_e32 v23, 0xffff0000, v23
	v_rndne_f64_e32 v[58:59], v[58:59]
	v_cvt_pk_bf16_f32 v122, v28, v29
	v_lshlrev_b32_e32 v18, 16, v19
	v_and_b32_e32 v19, 0xffff0000, v19
	v_pk_mul_f32 v[28:29], v[36:37], v[22:23]
	v_pk_mul_f32 v[22:23], v[34:35], v[22:23]
	v_fma_f64 v[42:43], v[42:43], s[14:15], -v[58:59]
	v_pk_fma_f32 v[28:29], v[34:35], v[18:19], v[28:29]
	v_pk_fma_f32 v[18:19], v[36:37], v[18:19], v[22:23] neg_lo:[0,0,1] neg_hi:[0,0,1]
	v_cvt_f32_f64_e32 v43, v[42:43]
	v_pk_mul_f32 v[28:29], v[28:29], s[16:17] op_sel_hi:[1,0]
	v_pk_mul_f32 v[18:19], v[18:19], s[16:17] op_sel_hi:[1,0]
	v_lshlrev_b32_e32 v22, 16, v24
	v_and_b32_e32 v23, 0xffff0000, v24
	v_sin_f32_e32 v42, v43
	v_cos_f32_e32 v44, v43
	v_sin_f32_e32 v43, v0
	v_cos_f32_e32 v45, v0
	v_cvt_pk_bf16_f32 v119, v28, v29
	v_cvt_pk_bf16_f32 v123, v18, v19
	v_lshlrev_b32_e32 v18, 16, v20
	v_and_b32_e32 v19, 0xffff0000, v20
	v_pk_mul_f32 v[28:29], v[40:41], v[22:23]
	v_pk_mul_f32 v[22:23], v[38:39], v[22:23]
	v_pk_fma_f32 v[28:29], v[38:39], v[18:19], v[28:29]
	v_pk_fma_f32 v[18:19], v[40:41], v[18:19], v[22:23] neg_lo:[0,0,1] neg_hi:[0,0,1]
	v_lshlrev_b32_e32 v20, 16, v25
	v_pk_mul_f32 v[18:19], v[18:19], s[16:17] op_sel_hi:[1,0]
	v_pk_mul_f32 v[50:51], v[50:51], s[16:17] op_sel_hi:[1,0]
	v_cvt_pk_bf16_f32 v124, v18, v19
	v_lshlrev_b32_e32 v18, 16, v21
	v_and_b32_e32 v19, 0xffff0000, v21
	v_and_b32_e32 v21, 0xffff0000, v25
	v_pk_mul_f32 v[22:23], v[44:45], v[20:21]
	v_pk_mul_f32 v[20:21], v[42:43], v[20:21]
	v_pk_fma_f32 v[22:23], v[42:43], v[18:19], v[22:23]
	v_pk_fma_f32 v[18:19], v[44:45], v[18:19], v[20:21] neg_lo:[0,0,1] neg_hi:[0,0,1]
	v_pk_mul_f32 v[28:29], v[28:29], s[16:17] op_sel_hi:[1,0]
	v_pk_mul_f32 v[18:19], v[18:19], s[16:17] op_sel_hi:[1,0]
	v_pk_mul_f32 v[22:23], v[22:23], s[16:17] op_sel_hi:[1,0]
	v_cvt_pk_bf16_f32 v125, v18, v19
	v_lshlrev_b32_e32 v18, 16, v14
	v_and_b32_e32 v19, 0xffff0000, v14
	v_pk_mul_f32 v[18:19], v[18:19], s[16:17] op_sel_hi:[1,0]
	v_lshlrev_b32_e32 v14, 16, v15
	v_cvt_pk_bf16_f32 v126, v18, v19
	v_add_co_u32_e32 v18, vcc, s28, v194
	v_and_b32_e32 v15, 0xffff0000, v15
	s_nop 0
	v_addc_co_u32_e32 v19, vcc, 0, v195, vcc
	v_add_co_u32_e32 v20, vcc, s28, v190
	v_pk_mul_f32 v[14:15], v[14:15], s[16:17] op_sel_hi:[1,0]
	s_nop 0
	v_addc_co_u32_e32 v21, vcc, 0, v191, vcc
	global_load_dwordx4 v[138:141], v[18:19], off
	global_load_dwordx4 v[142:145], v[20:21], off
	v_cvt_pk_bf16_f32 v127, v14, v15
	v_lshlrev_b32_e32 v14, 16, v16
	v_and_b32_e32 v15, 0xffff0000, v16
	v_pk_mul_f32 v[14:15], v[14:15], s[16:17] op_sel_hi:[1,0]
	v_cvt_pk_bf16_f32 v118, v50, v51
	v_cvt_pk_bf16_f32 v128, v14, v15
	v_lshlrev_b32_e32 v14, 16, v17
	v_and_b32_e32 v15, 0xffff0000, v17
	v_pk_mul_f32 v[14:15], v[14:15], s[16:17] op_sel_hi:[1,0]
	v_cvt_pk_bf16_f32 v120, v28, v29
	v_cvt_pk_bf16_f32 v129, v14, v15
	s_waitcnt vmcnt(8)
	v_lshlrev_b32_e32 v14, 16, v10
	v_and_b32_e32 v15, 0xffff0000, v10
	v_lshlrev_b32_e32 v10, 16, v11
	v_and_b32_e32 v11, 0xffff0000, v11
	v_pk_mul_f32 v[10:11], v[10:11], s[16:17] op_sel_hi:[1,0]
	v_pk_mul_f32 v[14:15], v[14:15], s[16:17] op_sel_hi:[1,0]
	v_cvt_pk_bf16_f32 v147, v10, v11
	v_lshlrev_b32_e32 v10, 16, v12
	v_and_b32_e32 v11, 0xffff0000, v12
	v_pk_mul_f32 v[10:11], v[10:11], s[16:17] op_sel_hi:[1,0]
	v_cvt_pk_bf16_f32 v146, v14, v15
	v_cvt_pk_bf16_f32 v148, v10, v11
	v_lshlrev_b32_e32 v10, 16, v13
	v_and_b32_e32 v11, 0xffff0000, v13
	v_pk_mul_f32 v[10:11], v[10:11], s[16:17] op_sel_hi:[1,0]
	v_mov_b32_e32 v14, v1
	v_cvt_pk_bf16_f32 v149, v10, v11
	v_lshlrev_b32_e32 v10, 16, v6
	v_and_b32_e32 v11, 0xffff0000, v6
	v_lshlrev_b32_e32 v6, 16, v7
	v_and_b32_e32 v7, 0xffff0000, v7
	v_pk_mul_f32 v[6:7], v[6:7], s[16:17] op_sel_hi:[1,0]
	v_pk_mul_f32 v[10:11], v[10:11], s[16:17] op_sel_hi:[1,0]
	v_cvt_pk_bf16_f32 v151, v6, v7
	v_lshlrev_b32_e32 v6, 16, v8
	v_and_b32_e32 v7, 0xffff0000, v8
	v_pk_mul_f32 v[6:7], v[6:7], s[16:17] op_sel_hi:[1,0]
	v_mov_b32_e32 v15, v1
	v_cvt_pk_bf16_f32 v152, v6, v7
	v_lshlrev_b32_e32 v6, 16, v9
	v_and_b32_e32 v7, 0xffff0000, v9
	v_pk_mul_f32 v[6:7], v[6:7], s[16:17] op_sel_hi:[1,0]
	v_cvt_pk_bf16_f32 v121, v22, v23
	v_cvt_pk_bf16_f32 v153, v6, v7
	s_waitcnt vmcnt(4)
	v_lshlrev_b32_e32 v6, 16, v2
	v_and_b32_e32 v7, 0xffff0000, v2
	v_lshlrev_b32_e32 v2, 16, v3
	v_and_b32_e32 v3, 0xffff0000, v3
	v_pk_mul_f32 v[2:3], v[2:3], s[16:17] op_sel_hi:[1,0]
	v_pk_mul_f32 v[6:7], v[6:7], s[16:17] op_sel_hi:[1,0]
	v_cvt_pk_bf16_f32 v155, v2, v3
	v_lshlrev_b32_e32 v2, 16, v4
	v_and_b32_e32 v3, 0xffff0000, v4
	v_pk_mul_f32 v[2:3], v[2:3], s[16:17] op_sel_hi:[1,0]
	v_cvt_pk_bf16_f32 v150, v10, v11
	v_cvt_pk_bf16_f32 v156, v2, v3
	v_lshlrev_b32_e32 v2, 16, v5
	v_and_b32_e32 v3, 0xffff0000, v5
	v_pk_mul_f32 v[2:3], v[2:3], s[16:17] op_sel_hi:[1,0]
	v_cvt_pk_bf16_f32 v154, v6, v7
	v_cvt_pk_bf16_f32 v157, v2, v3
	v_mov_b32_e32 v0, v1
	v_mov_b32_e32 v2, v1
	v_mov_b32_e32 v3, v1
	v_mov_b32_e32 v4, v1
	v_mov_b32_e32 v5, v1
	v_mov_b32_e32 v6, v1
	v_mov_b32_e32 v7, v1
	v_mov_b32_e32 v8, v1
	v_mov_b32_e32 v9, v1
	v_mov_b32_e32 v10, v1
	v_mov_b32_e32 v11, v1
	v_mov_b32_e32 v12, v1
	v_mov_b32_e32 v13, v1
	v_mov_b64_e32 v[46:47], v[14:15]
	v_mov_b64_e32 v[30:31], v[14:15]
	v_mov_b64_e32 v[64:65], v[14:15]
	v_mov_b64_e32 v[44:45], v[12:13]
	v_mov_b64_e32 v[42:43], v[10:11]
	v_mov_b64_e32 v[40:41], v[8:9]
	v_mov_b64_e32 v[38:39], v[6:7]
	v_mov_b64_e32 v[36:37], v[4:5]
	v_mov_b64_e32 v[34:35], v[2:3]
	v_mov_b64_e32 v[32:33], v[0:1]
	v_mov_b64_e32 v[28:29], v[12:13]
	v_mov_b64_e32 v[26:27], v[10:11]
	v_mov_b64_e32 v[24:25], v[8:9]
	v_mov_b64_e32 v[22:23], v[6:7]
	v_mov_b64_e32 v[20:21], v[4:5]
	v_mov_b64_e32 v[18:19], v[2:3]
	v_mov_b64_e32 v[16:17], v[0:1]
	v_mov_b64_e32 v[62:63], v[12:13]
	v_mov_b64_e32 v[60:61], v[10:11]
	v_mov_b64_e32 v[58:59], v[8:9]
	v_mov_b64_e32 v[56:57], v[6:7]
	v_mov_b64_e32 v[54:55], v[4:5]
	v_mov_b64_e32 v[52:53], v[2:3]
	v_mov_b64_e32 v[50:51], v[0:1]
	v_mov_b32_e32 v2, 0
	s_branch .LBB0_849
